# MLA tile loop: always-true exec guard around the first key-chunk load/store removed, branch around the per-wave all-or-nothing second chunk removed (4 branches and 5 other scalar instructions fewer pe
# speedup vs baseline: 1.0069x; 1.0069x over previous
;     ...
;     auto gload = [&](int j) {
; #pragma unroll
;         for (int r = 0; r < NK2; ++r) {
;             const int c = tid + NT * r;
;             if (c < 64 * KCH) { const int row = c / KCH, ch = c - row * KCH; kr[r] = *(const u32x4*)(kbase + (size_t)(64 * j + row) * ldk + ch * 8); }
;         }
;         { const int row = tid >> 3, ch = tid & 7; vr = *(const u32x4*)(vt + (size_t)row * LP + 64 * j + ch * 8); }
;         if (FOX) { if (tid < 64) br = bias[64 * j + tid]; }
;     };
;     ...
;         if (j > 0) gload(j - 1);
.LBB0_748:
	s_cmp_gt_i32 s2, 0
	s_cselect_b64 s[64:65], -1, 0
	s_cmp_lt_i32 s2, 1
	s_cbranch_scc1 .Lmp_lastG
	global_load_dwordx4 v[90:93], v[176:177], off
	s_and_saveexec_b64 s[8:9], s[6:7]
	global_load_dwordx4 v[94:97], v[178:179], off
	s_or_b64 exec, exec, s[8:9]
	v_lshl_add_u64 v[34:35], s[42:43], 1, v[162:163]
	global_load_dwordx4 v[98:101], v[34:35], off

;     ...
;     auto lstore = [&](int st) {
;         unsigned char* base = lds + st * STG;
; #pragma unroll
;         for (int r = 0; r < NK2; ++r) {
;             const int c = tid + NT * r;
;             if (c < 64 * KCH) { const int row = c / KCH, ch = c - row * KCH; *(u32x4*)(base + row * KROW + ch * 16) = kr[r]; }
;         }
;         { const int row = tid >> 3, ch = tid & 7; unsigned char* d = base + KBYTES + row * VROW + ch * 16;
;           *(u32x2*)d = (u32x2){vr[0], vr[1]}; *(u32x2*)(d + 8) = (u32x2){vr[2], vr[3]}; }
;         if (FOX) { if (tid < 64) *(float*)(base + KBYTES + VBYTES + tid * 4) = br; }
;     };
;     ...
;         if (j > 0) lstore(st ^ 1);
.LBB0_760:
	s_or_b64 exec, exec, s[66:67]
	s_andn2_b64 vcc, exec, s[64:65]
	s_cbranch_vccnz .Lmp_last
	s_xor_b32 s8, s61, 1
	s_mulk_i32 s8, 0x5700
	s_add_i32 s10, s8, 0
	v_add3_u32 v1, s10, v196, v197
	s_waitcnt vmcnt(1)
	ds_write_b128 v1, v[90:93] offset:2048
	s_and_saveexec_b64 s[8:9], s[6:7]
	v_add3_u32 v1, s10, v198, v199
	ds_write_b128 v1, v[94:97] offset:2048
	s_branch .LBB0_746
	s_nop 0
